# P0 ff1 / ff2 weight convert: next tile's cache lines touched one tile ahead (it+256 is a constant 4 MiB further), eight dummy dword loads per lane
# speedup vs baseline: 1.0085x; 1.0066x over previous
; DEVI unsigned pk_bf16(float lo, float hi) { unsigned r; asm("v_cvt_pk_bf16_f32 %0, %1, %2" : "=v"(r) : "v"(lo), "v"(hi)); return r; }
; DEVI int otid() { int t = threadIdx.x; asm volatile("" : "+v"(t)); return t; }
; DEVI int obid() { int t = blockIdx.x; asm volatile("" : "+s"(t)); return t; }
; __device__ __forceinline__ void wconv(unsigned char* lds, const float* __restrict__ src, bf16_t* __restrict__ dst, int K, int Nsrc, int Ndst, int mode, int nbatch) {
;   float* tile = (float*)lds;
;   const int tid = otid();
;   const int tk = K >> 6, tn = Ndst >> 6, per = tk * tn, total = per * nbatch;
;   for (int it = obid(); it < total; it += gridDim.x) {
;     const int bi = it / per, rem = it - bi * per, kt = rem / tn, nt = rem - kt * tn;
;     const float* s = src + (size_t)bi * K * Nsrc; bf16_t* d = dst + (size_t)bi * Ndst * K;
;     const int nn = tid & 63, dcol = nt * 64 + nn;
;     int scol; float scale = 1.f;
;     if (mode == 0) scol = dcol < Nsrc ? dcol : -1;
;     else {
;       if (dcol < 2048) { scol = dcol; if (dcol >= 512 && dcol < 1024) scale = 0.08838834764831845f; }
;       else if (dcol < 3072) scol = dcol - 2048 + 3080;
;       else if (dcol < 4096) scol = dcol - 3072 + 2048;
;       else if (dcol < 5120) scol = dcol - 4096 + 4104;
;       else if (dcol < 5128) scol = dcol - 5120 + 3072;
;       else scol = -1;
;     }
;     __syncthreads();
; #pragma unroll
;     for (int i = 0; i < 8; ++i) {
;       const int kk = (tid >> 6) + 8 * i;
;       float v = 0.f; if (scol >= 0) v = s[(size_t)(kt * 64 + kk) * Nsrc + scol] * scale;
;       tile[kk * 65 + nn] = v;
;     }
;     __syncthreads();
;     {
;       const int q = tid, n2 = q >> 3, kc = q & 7;
;       float v[8];
; #pragma unroll
;       for (int j = 0; j < 8; ++j) v[j] = tile[(kc * 8 + j) * 65 + n2];
;       uint4 w = make_uint4(pk_bf16(v[0], v[1]), pk_bf16(v[2], v[3]), pk_bf16(v[4], v[5]), pk_bf16(v[6], v[7]));
;       *(uint4*)(d + (size_t)(nt * 64 + n2) * K + kt * 64 + kc * 8) = w;
;     }
.LBB0_52:
	s_or_b64 exec, exec, s[8:9]
	s_lshl_b64 s[6:7], s[6:7], 22
	s_sub_i32 s3, 0, s16
	s_lshl_b64 s[6:7], s[6:7], 1
	v_readlane_b32 s4, v253, 60
	s_add_u32 s6, s4, s6
	s_waitcnt vmcnt(1)
	ds_write_b32 v14, v2 offset:12480
	s_waitcnt vmcnt(0)
	ds_write_b32 v14, v17 offset:14560
	s_waitcnt lgkmcnt(0)
	s_barrier
	ds_read2_b32 v[6:7], v15 offset1:65
	ds_read2_b32 v[20:21], v15 offset0:130 offset1:195
	ds_read2_b32 v[22:23], v16 offset0:4 offset1:69
	ds_read2_b32 v[24:25], v16 offset0:134 offset1:199
	v_readlane_b32 s4, v253, 61
	s_addc_u32 s7, s4, s7
	s_add_i32 s98, s12, s52
	s_cmp_eq_u32 s52, 0x100
	s_cselect_b32 s99, 0x800, 0
	s_cmp_lt_i32 s98, s99
	s_cselect_b32 s98, 0x380000, 0
	s_cselect_b32 s100, 0x80000, 0
	s_mov_b32 s99, 0
	s_mov_b32 s101, 0
	v_lshl_add_u64 v[54:55], v[40:41], 0, s[98:99]
	global_load_dword v58, v[54:55], off
	v_lshl_add_u64 v[56:57], v[54:55], 0, s[100:101]
	global_load_dword v59, v[56:57], off
	v_lshl_add_u64 v[54:55], v[42:43], 0, s[98:99]
	global_load_dword v58, v[54:55], off
	v_lshl_add_u64 v[56:57], v[54:55], 0, s[100:101]
	global_load_dword v59, v[56:57], off
	v_lshl_add_u64 v[54:55], v[44:45], 0, s[98:99]
	global_load_dword v58, v[54:55], off
	v_lshl_add_u64 v[56:57], v[54:55], 0, s[100:101]
	global_load_dword v59, v[56:57], off
	v_lshl_add_u64 v[54:55], v[48:49], 0, s[98:99]
	global_load_dword v58, v[54:55], off
	v_lshl_add_u64 v[56:57], v[54:55], 0, s[100:101]
	global_load_dword v59, v[56:57], off
	s_add_i32 s3, s3, s13
	s_waitcnt lgkmcnt(3)
	v_cvt_pk_bf16_f32 v18, v6, v7
	v_add_u32_e32 v6, s3, v9
	v_ashrrev_i32_e32 v7, 31, v6
	v_lshlrev_b64 v[6:7], 11, v[6:7]
	v_lshl_add_u64 v[6:7], s[6:7], 0, v[6:7]
	s_ashr_i32 s3, s2, 31
	v_lshl_add_u64 v[6:7], s[2:3], 1, v[6:7]
	s_add_i32 s12, s12, s52
	s_add_i32 s13, s13, s14
	v_lshl_add_u64 v[6:7], v[6:7], 0, v[4:5]
	s_cmpk_lt_i32 s12, 0x800
	s_waitcnt lgkmcnt(2)
	v_cvt_pk_bf16_f32 v19, v20, v21
	s_waitcnt lgkmcnt(1)
	v_cvt_pk_bf16_f32 v20, v22, v23
	s_waitcnt lgkmcnt(0)
	v_cvt_pk_bf16_f32 v21, v24, v25
	global_store_dwordx4 v[6:7], v[18:21], off
	s_cbranch_scc0 .LBB0_61

; DEVI unsigned pk_bf16(float lo, float hi) { unsigned r; asm("v_cvt_pk_bf16_f32 %0, %1, %2" : "=v"(r) : "v"(lo), "v"(hi)); return r; }
; DEVI int otid() { int t = threadIdx.x; asm volatile("" : "+v"(t)); return t; }
; DEVI int obid() { int t = blockIdx.x; asm volatile("" : "+s"(t)); return t; }
; __device__ __forceinline__ void wconv(unsigned char* lds, const float* __restrict__ src, bf16_t* __restrict__ dst, int K, int Nsrc, int Ndst, int mode, int nbatch) {
;   float* tile = (float*)lds;
;   const int tid = otid();
;   const int tk = K >> 6, tn = Ndst >> 6, per = tk * tn, total = per * nbatch;
;   for (int it = obid(); it < total; it += gridDim.x) {
;     const int bi = it / per, rem = it - bi * per, kt = rem / tn, nt = rem - kt * tn;
;     const float* s = src + (size_t)bi * K * Nsrc; bf16_t* d = dst + (size_t)bi * Ndst * K;
;     const int nn = tid & 63, dcol = nt * 64 + nn;
;     int scol; float scale = 1.f;
;     if (mode == 0) scol = dcol < Nsrc ? dcol : -1;
;     else {
;       if (dcol < 2048) { scol = dcol; if (dcol >= 512 && dcol < 1024) scale = 0.08838834764831845f; }
;       else if (dcol < 3072) scol = dcol - 2048 + 3080;
;       else if (dcol < 4096) scol = dcol - 3072 + 2048;
;       else if (dcol < 5120) scol = dcol - 4096 + 4104;
;       else if (dcol < 5128) scol = dcol - 5120 + 3072;
;       else scol = -1;
;     }
;     __syncthreads();
; #pragma unroll
;     for (int i = 0; i < 8; ++i) {
;       const int kk = (tid >> 6) + 8 * i;
;       float v = 0.f; if (scol >= 0) v = s[(size_t)(kt * 64 + kk) * Nsrc + scol] * scale;
;       tile[kk * 65 + nn] = v;
;     }
;     __syncthreads();
;     {
;       const int q = tid, n2 = q >> 3, kc = q & 7;
;       float v[8];
; #pragma unroll
;       for (int j = 0; j < 8; ++j) v[j] = tile[(kc * 8 + j) * 65 + n2];
;       uint4 w = make_uint4(pk_bf16(v[0], v[1]), pk_bf16(v[2], v[3]), pk_bf16(v[4], v[5]), pk_bf16(v[6], v[7]));
;       *(uint4*)(d + (size_t)(nt * 64 + n2) * K + kt * 64 + kc * 8) = w;
;     }
.LBB0_63:
	s_or_b64 exec, exec, s[8:9]
	s_lshl_b64 s[6:7], s[6:7], 22
	s_sub_i32 s3, 0, s16
	s_lshl_b64 s[6:7], s[6:7], 1
	v_readlane_b32 s4, v253, 62
	s_add_u32 s6, s4, s6
	s_waitcnt vmcnt(1)
	ds_write_b32 v14, v2 offset:12480
	s_waitcnt vmcnt(0)
	ds_write_b32 v14, v17 offset:14560
	s_waitcnt lgkmcnt(0)
	s_barrier
	ds_read2_b32 v[6:7], v15 offset1:65
	ds_read2_b32 v[20:21], v15 offset0:130 offset1:195
	ds_read2_b32 v[22:23], v16 offset0:4 offset1:69
	ds_read2_b32 v[24:25], v16 offset0:134 offset1:199
	v_readlane_b32 s4, v253, 63
	s_addc_u32 s7, s4, s7
	s_add_i32 s98, s12, s52
	s_cmp_eq_u32 s52, 0x100
	s_cselect_b32 s99, 0x800, 0
	s_cmp_lt_i32 s98, s99
	s_cselect_b32 s98, 0x3e0000, 0
	s_cselect_b32 s100, 0x20000, 0
	s_mov_b32 s99, 0
	s_mov_b32 s101, 0
	v_lshl_add_u64 v[54:55], v[40:41], 0, s[98:99]
	global_load_dword v58, v[54:55], off
	v_lshl_add_u64 v[56:57], v[54:55], 0, s[100:101]
	global_load_dword v59, v[56:57], off
	v_lshl_add_u64 v[54:55], v[42:43], 0, s[98:99]
	global_load_dword v58, v[54:55], off
	v_lshl_add_u64 v[56:57], v[54:55], 0, s[100:101]
	global_load_dword v59, v[56:57], off
	v_lshl_add_u64 v[54:55], v[44:45], 0, s[98:99]
	global_load_dword v58, v[54:55], off
	v_lshl_add_u64 v[56:57], v[54:55], 0, s[100:101]
	global_load_dword v59, v[56:57], off
	v_lshl_add_u64 v[54:55], v[48:49], 0, s[98:99]
	global_load_dword v58, v[54:55], off
	v_lshl_add_u64 v[56:57], v[54:55], 0, s[100:101]
	global_load_dword v59, v[56:57], off
	s_add_i32 s3, s3, s13
	s_waitcnt lgkmcnt(3)
	v_cvt_pk_bf16_f32 v18, v6, v7
	v_add_u32_e32 v6, s3, v9
	v_ashrrev_i32_e32 v7, 31, v6
	v_lshlrev_b64 v[6:7], 13, v[6:7]
	v_lshl_add_u64 v[6:7], s[6:7], 0, v[6:7]
	s_ashr_i32 s3, s2, 31
	v_lshl_add_u64 v[6:7], s[2:3], 1, v[6:7]
	s_add_i32 s12, s12, s52
	s_add_i32 s13, s13, s14
	v_lshl_add_u64 v[6:7], v[6:7], 0, v[4:5]
	s_cmpk_lt_i32 s12, 0x800
	s_waitcnt lgkmcnt(2)
	v_cvt_pk_bf16_f32 v19, v20, v21
	s_waitcnt lgkmcnt(1)
	v_cvt_pk_bf16_f32 v20, v22, v23
	s_waitcnt lgkmcnt(0)
	v_cvt_pk_bf16_f32 v21, v24, v25
	global_store_dwordx4 v[6:7], v[18:21], off
	s_cbranch_scc0 .LBB0_72
